# baseline (speedup 1.0000x reference)
;     __host__ __device__ bool next(int i, Unit& u) const {
;         int ii = i; if (rounds) { if (i >= rounds) return false; ii = i + rot; if (ii >= rounds) ii -= rounds; }
;         const long L = (long)ii * G + c; if (L >= nwg) return false;
;         int wgid = (int)L; { const int q = nwg / NXCD, r = nwg % NXCD, xcd = wgid % NXCD, off = wgid / NXCD; wgid = (xcd < r ? xcd * (q + 1) : r * (q + 1) + (xcd - r) * q) + off; }
;         const int nig = WGM * nN, gid = wgid / nig, fm = gid * WGM, gsz = (nM - fm) < WGM ? (nM - fm) : WGM;
;         u.pm = fm + ((wgid % nig) % gsz); u.pn = (wgid % nig) / gsz; return true;
;     }
.LBB0_125:
	s_mov_b64 s[68:69], 0
	s_and_b64 vcc, exec, s[14:15]
	s_cbranch_vccz .LBB0_128
	s_mul_hi_i32 s2, s11, s4
	s_mul_i32 s11, s11, s4
	s_add_u32 s14, s11, s23
	v_readlane_b32 s11, v254, 44
	s_addc_u32 s15, s2, s11
	v_cmp_gt_i64_e32 vcc, s[14:15], v[240:241]
	s_cbranch_vccnz .LBB0_128
	s_cmp_lg_u32 s4, 0x100
	s_cbranch_scc1 .Lnx1_gen
	s_lshr_b32 s2, s14, 8
	s_lshl_b32 s2, s2, 2
	s_bfe_u32 s11, s14, 0x20006
	s_add_i32 s64, s2, s11
	s_and_b32 s2, s14, 7
	s_lshl_b32 s2, s2, 3
	s_bfe_u32 s11, s14, 0x30003
	s_add_i32 s66, s2, s11
	s_mov_b64 s[68:69], -1
	s_branch .LBB0_128
.Lnx1_gen:
	s_ashr_i32 s2, s14, 31
	s_lshr_b32 s2, s2, 29
	s_add_i32 s2, s14, s2
	s_ashr_i32 s11, s2, 3
	s_and_b32 s2, s2, -8
	s_sub_i32 s2, s14, s2
	s_cmp_lt_i32 s2, 0
	s_movk_i32 s14, 0x1a1
	s_cselect_b32 s14, s14, 0x1a0
	s_mul_i32 s2, s2, s14
	s_add_i32 s2, s2, s11
	s_mul_hi_i32 s11, s2, 0x4ec4ec4f
	s_lshr_b32 s14, s11, 31
	s_ashr_i32 s11, s11, 7
	s_add_i32 s11, s11, s14
	s_lshl_b32 s14, s11, 3
	s_sub_i32 s15, 64, s14
	s_min_i32 s15, s15, 8
	s_abs_i32 s18, s15
	v_cvt_f32_u32_e32 v0, s18
	s_sub_i32 s34, 0, s18
	s_mulk_i32 s11, 0x1a0
	s_sub_i32 s2, s2, s11
	v_rcp_iflag_f32_e32 v0, v0
	s_abs_i32 s11, s2
	s_xor_b32 s19, s2, s15
	s_ashr_i32 s19, s19, 31
	v_mul_f32_e32 v0, 0x4f7ffffe, v0
	v_cvt_u32_f32_e32 v0, v0
	s_mov_b64 s[68:69], -1
	v_readfirstlane_b32 s41, v0
	s_mul_i32 s34, s34, s41
	s_mul_hi_u32 s34, s41, s34
	s_add_i32 s41, s41, s34
	s_mul_hi_u32 s34, s11, s41
	s_mul_i32 s41, s34, s18
	s_sub_i32 s11, s11, s41
	s_add_i32 s42, s34, 1
	s_sub_i32 s41, s11, s18
	s_cmp_ge_u32 s11, s18
	s_cselect_b32 s34, s42, s34
	s_cselect_b32 s11, s41, s11
	s_add_i32 s41, s34, 1
	s_cmp_ge_u32 s11, s18
	s_cselect_b32 s11, s41, s34
	s_xor_b32 s11, s11, s19
	s_sub_i32 s64, s11, s19
	s_mul_i32 s11, s64, s15
	s_sub_i32 s2, s2, s11
	s_add_i32 s66, s14, s2

;     __host__ __device__ bool next(int i, Unit& u) const {
;         int ii = i; if (rounds) { if (i >= rounds) return false; ii = i + rot; if (ii >= rounds) ii -= rounds; }
;         const long L = (long)ii * G + c; if (L >= nwg) return false;
;         int wgid = (int)L; { const int q = nwg / NXCD, r = nwg % NXCD, xcd = wgid % NXCD, off = wgid / NXCD; wgid = (xcd < r ? xcd * (q + 1) : r * (q + 1) + (xcd - r) * q) + off; }
;         const int nig = WGM * nN, gid = wgid / nig, fm = gid * WGM, gsz = (nM - fm) < WGM ? (nM - fm) : WGM;
;         u.pm = fm + ((wgid % nig) % gsz); u.pn = (wgid % nig) / gsz; return true;
;     }
.LBB0_727:
	s_add_i32 s58, s58, 1
	s_mul_i32 s12, s58, s55
	s_mul_hi_u32 s13, s58, s38
	s_add_i32 s13, s13, s12
	s_mul_i32 s12, s58, s38
	s_add_u32 s12, s12, s23
	v_readlane_b32 s24, v254, 44
	s_addc_u32 s13, s13, s24
	v_cmp_gt_i64_e32 vcc, s[12:13], v[244:245]
	v_cmp_lt_i64_e64 s[42:43], s[12:13], v[242:243]
	s_cbranch_vccnz .LBB0_729
	s_cmp_lg_u32 s38, 0x100
	s_cbranch_scc1 .Lnx8_gen
	s_lshr_b32 s13, s12, 8
	s_lshl_b32 s13, s13, 2
	s_bfe_u32 s24, s12, 0x20006
	s_add_i32 s46, s13, s24
	s_and_b32 s13, s12, 7
	s_lshl_b32 s13, s13, 3
	s_bfe_u32 s24, s12, 0x30003
	s_add_i32 s48, s13, s24
	s_branch .LBB0_729
.Lnx8_gen:
	s_ashr_i32 s13, s12, 31
	s_lshr_b32 s13, s13, 29
	s_add_i32 s13, s12, s13
	s_ashr_i32 s24, s13, 3
	s_and_b32 s13, s13, -8
	s_sub_i32 s12, s12, s13
	s_cmp_lt_i32 s12, 0
	s_movk_i32 s13, 0x161
	s_cselect_b32 s13, s13, 0x160
	s_mul_i32 s12, s12, s13
	s_add_i32 s12, s12, s24
	s_mul_hi_i32 s13, s12, 0x2e8ba2e9
	s_lshr_b32 s24, s13, 31
	s_ashr_i32 s13, s13, 6
	s_add_i32 s13, s13, s24
	s_lshl_b32 s24, s13, 3
	s_sub_i32 s25, 64, s24
	s_min_i32 s25, s25, 8
	s_abs_i32 s33, s25
	v_cvt_f32_u32_e32 v0, s33
	s_sub_i32 s47, 0, s33
	s_mulk_i32 s13, 0x160
	s_sub_i32 s12, s12, s13
	v_rcp_iflag_f32_e32 v0, v0
	s_abs_i32 s13, s12
	s_xor_b32 s46, s12, s25
	s_ashr_i32 s46, s46, 31
	v_mul_f32_e32 v0, 0x4f7ffffe, v0
	v_cvt_u32_f32_e32 v0, v0
	s_nop 0
	v_readfirstlane_b32 s48, v0
	s_mul_i32 s47, s47, s48
	s_mul_hi_u32 s47, s48, s47
	s_add_i32 s48, s48, s47
	s_mul_hi_u32 s47, s13, s48
	s_mul_i32 s48, s47, s33
	s_sub_i32 s13, s13, s48
	s_add_i32 s49, s47, 1
	s_sub_i32 s48, s13, s33
	s_cmp_ge_u32 s13, s33
	s_cselect_b32 s47, s49, s47
	s_cselect_b32 s13, s48, s13
	s_add_i32 s48, s47, 1
	s_cmp_ge_u32 s13, s33
	s_cselect_b32 s13, s48, s47
	s_xor_b32 s13, s13, s46
	s_sub_i32 s46, s13, s46
	s_mul_i32 s13, s46, s25
	s_sub_i32 s12, s12, s13
	s_add_i32 s48, s24, s12
